# v7 + grid barrier: census counter loads all in flight (one wait), non-leader workgroups watch the cross-XCD generation word directly (strategy: prologue de-serialisation of the barrier)
# speedup vs baseline: 1.0053x; 1.0053x over previous
.LBB0_568:
	global_load_dword v2, v161, s[34:35] sc1
	s_waitcnt lgkmcnt(0)
	global_load_dword v0, v161, s[34:35] offset:256 sc1
	global_load_dword v1, v161, s[34:35] offset:512 sc1
	global_load_dword v3, v161, s[34:35] offset:768 sc1
	global_load_dword v4, v161, s[34:35] offset:1024 sc1
	global_load_dword v5, v161, s[34:35] offset:1280 sc1
	global_load_dword v6, v161, s[34:35] offset:1536 sc1
	global_load_dword v7, v161, s[34:35] offset:1792 sc1
	global_load_dword v8, v161, s[34:35] offset:2048 sc1
	global_load_dword v9, v161, s[34:35] offset:2304 sc1
	global_load_dword v10, v161, s[34:35] offset:2560 sc1
	global_load_dword v11, v161, s[34:35] offset:2816 sc1
	global_load_dword v12, v161, s[34:35] offset:3072 sc1
	global_load_dword v13, v161, s[34:35] offset:3328 sc1
	global_load_dword v14, v161, s[34:35] offset:3584 sc1
	global_load_dword v15, v161, s[34:35] offset:3840 sc1
	s_mov_b64 s[4:5], -1
	s_waitcnt vmcnt(0)
	v_add_u32_e32 v16, v0, v2
	v_add_u32_e32 v16, v16, v1
	v_add_u32_e32 v16, v16, v3
	v_add_u32_e32 v16, v16, v4
	v_add_u32_e32 v16, v16, v5
	v_add_u32_e32 v16, v16, v6
	v_add_u32_e32 v16, v16, v7
	v_add_u32_e32 v16, v16, v8
	v_add_u32_e32 v16, v16, v9
	v_add_u32_e32 v16, v16, v10
	v_add_u32_e32 v16, v16, v11
	v_add_u32_e32 v16, v16, v12
	v_add_u32_e32 v16, v16, v13
	v_add_u32_e32 v16, v16, v14
	v_add_u32_e32 v16, v16, v15
	s_mov_b64 s[2:3], -1
	v_cmp_eq_u32_e32 vcc, s29, v16
	s_cbranch_vccnz .LBB0_567
	s_and_b32 s2, s9, 0xff
	s_cmp_eq_u32 s2, 0
	s_mov_b64 s[2:3], -1
	s_mov_b64 s[6:7], -1
	s_sleep 1
	s_cbranch_scc0 .LBB0_572
	global_load_dword v16, v161, s[30:31] sc1
	s_waitcnt vmcnt(0)
	v_cmp_eq_u32_e32 vcc, 0, v16
	s_cbranch_vccnz .LBB0_574
	s_mov_b64 s[6:7], 0

.LBB0_582:
	s_or_b64 exec, exec, s[2:3]
	v_cvt_f32_u32_e32 v4, v2
	s_waitcnt vmcnt(0)
	v_readfirstlane_b32 s2, v3
	v_sub_u32_e32 v3, 0, v2
	v_rcp_iflag_f32_e32 v4, v4
	v_add_u32_e32 v5, s2, v1
	v_mul_f32_e32 v4, 0x4f7ffffe, v4
	v_cvt_u32_f32_e32 v4, v4
	v_mul_lo_u32 v1, v3, v4
	v_mul_hi_u32 v1, v4, v1
	v_add_u32_e32 v1, v4, v1
	v_mul_hi_u32 v1, v5, v1
	v_mul_lo_u32 v3, v1, v2
	v_sub_u32_e32 v3, v5, v3
	v_add_u32_e32 v4, 1, v1
	v_cmp_ge_u32_e32 vcc, v3, v2
	s_nop 1
	v_cndmask_b32_e32 v1, v1, v4, vcc
	v_sub_u32_e32 v4, v3, v2
	v_cndmask_b32_e32 v3, v3, v4, vcc
	v_add_u32_e32 v4, 1, v1
	v_cmp_ge_u32_e32 vcc, v3, v2
	v_add_u32_e32 v3, 1, v5
	s_nop 0
	v_cndmask_b32_e32 v1, v1, v4, vcc
	v_mul_lo_u32 v4, v2, v1
	v_add_u32_e32 v2, v4, v2
	v_cmp_ne_u32_e32 vcc, v3, v2
	s_and_saveexec_b64 s[2:3], vcc
	s_xor_b64 s[2:3], exec, s[2:3]
	s_cbranch_execz .LBB0_596
	v_readlane_b32 s4, v255, 28
	v_readlane_b32 s5, v255, 29
	s_waitcnt lgkmcnt(0)
	s_nop 3
	global_load_dword v0, v161, s[4:5] sc1
	s_waitcnt vmcnt(0)
	v_cmp_eq_u32_e32 vcc, v0, v1
	s_and_saveexec_b64 s[4:5], vcc
	s_cbranch_execz .LBB0_595
	s_mov_b32 s19, 1
	s_mov_b64 s[6:7], 0
	s_branch .LBB0_586

.LBB0_590:
	v_readlane_b32 s10, v255, 28
	v_readlane_b32 s11, v255, 29
	s_add_i32 s19, s19, 1
	s_mov_b64 s[12:13], -1
	s_nop 2
	global_load_dword v0, v161, s[10:11] sc1
	s_waitcnt vmcnt(0)
	v_cmp_ne_u32_e32 vcc, v0, v1
	s_orn2_b64 s[10:11], vcc, exec
	s_branch .LBB0_585
